# P0 leftover XN rows moved to WGs 16-31
# speedup vs baseline: 1.0290x; 1.0035x over previous
.LBB0_88:
	s_cmpk_lt_i32 s42, 0x4080
	s_cbranch_scc0 .LBB0_103
	s_waitcnt vmcnt(3)
	v_lshlrev_b32_e32 v16, 4, v200
	s_waitcnt lgkmcnt(0)
	global_load_dwordx4 v[0:3], v16, s[50:51]
	global_load_dwordx4 v[4:7], v16, s[50:51] offset:1024
	global_load_dwordx4 v[8:11], v16, s[50:51] offset:2048
	global_load_dwordx4 v[12:15], v16, s[50:51] offset:3072
	v_mbcnt_lo_u32_b32 v16, -1, 0
	v_mbcnt_hi_u32_b32 v16, -1, v16
	v_and_b32_e32 v18, 64, v16
	v_add_u32_e32 v18, 64, v18
	v_xor_b32_e32 v19, 1, v16
	v_cmp_lt_i32_e32 vcc, v19, v18
	v_mov_b32_e32 v17, 0
	s_add_i32 s32, s42, 0x780
	s_and_b32 s32, s32, 0x7ff
	s_add_i32 s3, s32, 0xffffc000
	v_cndmask_b32_e32 v19, v16, v19, vcc
	v_lshlrev_b32_e32 v82, 2, v19
	v_xor_b32_e32 v19, 2, v16
	v_cmp_lt_i32_e32 vcc, v19, v18
	s_lshl_b32 s22, s86, 5
	s_lshl_b32 s23, s86, 4
	v_cndmask_b32_e32 v19, v16, v19, vcc
	v_lshlrev_b32_e32 v83, 2, v19
	v_xor_b32_e32 v19, 4, v16
	v_cmp_lt_i32_e32 vcc, v19, v18
	s_mul_i32 s24, s86, 24
	v_lshlrev_b32_e32 v88, 4, v200
	v_cndmask_b32_e32 v19, v16, v19, vcc
	v_lshlrev_b32_e32 v84, 2, v19
	v_xor_b32_e32 v19, 8, v16
	v_cmp_lt_i32_e32 vcc, v19, v18
	v_mov_b32_e32 v89, 0x3727c5ac
	s_mov_b64 s[0:1], 0x200
	v_cndmask_b32_e32 v19, v16, v19, vcc
	v_lshlrev_b32_e32 v85, 2, v19
	v_xor_b32_e32 v19, 16, v16
	v_cmp_lt_i32_e32 vcc, v19, v18
	s_mov_b64 s[4:5], 0x400
	s_mov_b64 s[6:7], 0x600
	v_cndmask_b32_e32 v19, v16, v19, vcc
	v_lshlrev_b32_e32 v86, 2, v19
	v_xor_b32_e32 v19, 32, v16
	v_cmp_lt_i32_e32 vcc, v19, v18
	s_nop 1
	v_cndmask_b32_e32 v16, v16, v19, vcc
	v_lshlrev_b32_e32 v87, 2, v16
	v_lshlrev_b32_e32 v16, 3, v200
	v_lshl_add_u64 v[80:81], s[80:81], 0, v[16:17]
	s_branch .LBB0_91
